# prep part 1 (fp8 tables + weight transposes) moved from the compress phase into the attention phase: half 0 runs it before attention, half 1 after conv
# speedup vs baseline: 1.0069x; 1.0069x over previous
; __device__ __forceinline__ unsigned xb_ld(unsigned* p)              { return __hip_atomic_load(p, __ATOMIC_RELAXED, __HIP_MEMORY_SCOPE_AGENT); }
; __device__ __forceinline__ unsigned xb_add(unsigned* p, unsigned v) { return __hip_atomic_fetch_add(p, v, __ATOMIC_RELAXED, __HIP_MEMORY_SCOPE_AGENT); }
; __device__ __forceinline__ void xcd_barrier_complete(unsigned* bar, unsigned x, unsigned& nloc, unsigned& nx) {
;     const unsigned G = gridDim.x * gridDim.y * gridDim.z;
;     unsigned sum, cnt, mine, sp = 0u;
;     for (;;) {
;         sum = 0u; cnt = 0u; mine = 0u;
; #pragma unroll
;         for (unsigned j = 0; j < 16; ++j) { const unsigned c = xb_ld(&bar[XB_XCNT(j)]); sum += c; cnt += (c > 0u) ? 1u : 0u; mine = (j == x) ? c : mine; }
; __device__ __forceinline__ void xcd_barrier(const XcdBarrier& b) {
;     asm volatile("s_waitcnt vmcnt(0)" ::: "memory");
;     __syncthreads();
;     if (threadIdx.x == 0) {
;         unsigned* bar = b.bar;
;         __builtin_amdgcn_s_waitcnt(0);
;         unsigned nloc = b.st[0], nx = b.st[1];
;         if (nloc == 0u) { xcd_barrier_complete(bar, b.x, nloc, nx); b.st[0] = nloc; b.st[1] = nx; }
;         const unsigned old = xb_add(&bar[XB_XSUB(b.x)], 1u);
;         const unsigned gen = old / nloc;
;         if (old + 1u == (gen + 1u) * nloc) {
.LBB0_350:
.LBB0_477:
	s_waitcnt vmcnt(0)
	s_waitcnt lgkmcnt(0)
	s_barrier
	s_and_saveexec_b64 s[0:1], s[58:59]
	s_cbranch_execz .LBB0_529
	v_mov_b32_e32 v0, 0
	s_waitcnt vmcnt(0) expcnt(0) lgkmcnt(0)
	ds_read_b32 v2, v0 offset:16
	ds_read_b32 v1, v0 offset:20
	s_waitcnt lgkmcnt(1)
	v_cmp_ne_u32_e32 vcc, 0, v2
	s_cbranch_vccnz .LBB0_493
	s_add_u32 s2, s86, 0xec80400
	s_addc_u32 s3, s87, 0
	s_add_u32 s4, s86, 0xec80600
	s_addc_u32 s5, s87, 0
	s_add_u32 s6, s86, 0xec80700
	s_addc_u32 s7, s87, 0
	s_add_u32 s8, s86, 0xec80800
	s_addc_u32 s9, s87, 0
	s_add_u32 s10, s86, 0xec80900
	s_addc_u32 s11, s87, 0
	s_add_u32 s12, s86, 0xec80a00
	s_addc_u32 s13, s87, 0
	s_add_u32 s14, s86, 0xec80b00
	s_addc_u32 s15, s87, 0
	s_add_u32 s16, s86, 0xec80c00
	s_addc_u32 s17, s87, 0
	s_add_u32 s18, s86, 0xec80d00
	s_addc_u32 s19, s87, 0
	s_add_u32 s20, s86, 0xec80e00
	s_addc_u32 s21, s87, 0
	s_add_u32 s22, s86, 0xec80f00
	s_addc_u32 s23, s87, 0
	s_add_u32 s24, s86, 0xec81000
	s_addc_u32 s25, s87, 0
	s_add_u32 s26, s86, 0xec81100
	s_addc_u32 s27, s87, 0
	s_add_u32 s28, s86, 0xec81200
	s_addc_u32 s29, s87, 0
	s_add_u32 s30, s86, 0xec81300
	s_addc_u32 s31, s87, 0
	s_add_u32 s34, s86, 0xec81400
	s_addc_u32 s35, s87, 0
	s_mul_i32 s44, s55, s60
	s_add_u32 s36, s86, 0xec81500
	s_mul_i32 s44, s44, s54
	s_addc_u32 s37, s87, 0
	s_mov_b32 s45, 1
	s_branch .LBB0_481

; DI int vb_id() { return (int)blockIdx.x + half_id() * (int)gridDim.x; }
; DI int vb_n() { return (int)gridDim.x * 2; }
; DI void phase_prep(const Params& p, char* smem, int part, int vb) {
;     ...
;   } else {
;     const int NITEMS = 1024 + 1024 + 128 + 128 + 256 + 512 + 32;
;     for (int it0 = vb; it0 < NITEMS; it0 += vb_n()) {
;       int it = it0;
;       if (it < 1024) {
;         int row = it * 16 + wave * 4;
;         fp8_rows<4>(p.pu + (size_t)row * 1024, (unsigned char*)(ws + WS_UBF) + (size_t)row * 1024, (float*)(ws + WS_SU) + row, lane);
;         continue;
;       }
;       it -= 1024;
;       if (it < 1024) {
;         int row = it * 16 + wave * 4;
;         fp8_rows<4>(p.pv + (size_t)row * 1024, (unsigned char*)(ws + WS_VBF) + (size_t)row * 1024, (float*)(ws + WS_SV) + row, lane);
;         continue;
;       }
;       it -= 1024;
; __global__ void __launch_bounds__(512) fwd_megakernel(Params p) {
;     ...
;   phase_prep(p, hsm, 1, (vb_id() + vb_n() - 128) % vb_n());
;   xcd_barrier(xb);
;   phase_mix(p, hsm);
.LBB0_529:
	v_writelane_b32 v253, s58, 32
	s_nop 1
	v_writelane_b32 v253, s59, 33
	v_writelane_b32 v253, s72, 34
	s_nop 1
	v_writelane_b32 v253, s73, 35
	v_writelane_b32 v253, s74, 36
	v_writelane_b32 v253, s75, 37
	v_writelane_b32 v253, s76, 38
	v_writelane_b32 v253, s77, 39
	v_writelane_b32 v253, s78, 40
	v_writelane_b32 v253, s79, 41
	v_writelane_b32 v253, s80, 42
	v_writelane_b32 v253, s81, 43
	v_writelane_b32 v253, s82, 44
	v_writelane_b32 v253, s83, 45
	v_writelane_b32 v253, s84, 46
	v_writelane_b32 v253, s85, 47
	v_writelane_b32 v253, s86, 48
	v_writelane_b32 v253, s87, 49
	s_or_b64 exec, exec, s[0:1]
	v_writelane_b32 v253, s60, 50
	v_writelane_b32 v253, s53, 51
	v_writelane_b32 v253, s56, 52
	v_readfirstlane_b32 s0, v211
	s_lshr_b32 s0, s0, 8
	v_writelane_b32 v253, s57, 53
	v_writelane_b32 v253, s54, 54
	s_mul_i32 s0, s0, s54
	s_add_i32 s94, s0, s52
	v_writelane_b32 v253, s55, 55
	s_cmpk_gt_i32 s94, 0x3ff
	s_waitcnt lgkmcnt(0)
	s_barrier
	v_writelane_b32 v253, s52, 56
	v_readfirstlane_b32 s0, v211
	s_nop 0
	s_lshr_b32 s0, s0, 8
	s_cmp_lg_u32 s0, 0
	s_cbranch_scc1 .Lp1a_exit
	v_readlane_b32 s74, v253, 36
	v_readlane_b32 s75, v253, 37
	v_readlane_b32 s76, v253, 38
	v_readlane_b32 s77, v253, 39
	v_readlane_b32 s78, v253, 40
	v_readlane_b32 s79, v253, 41
	v_readlane_b32 s80, v253, 42
	v_readlane_b32 s81, v253, 43
	v_readlane_b32 s86, v253, 48
	v_readlane_b32 s87, v253, 49
	s_nop 3
	s_abs_i32 s1, s88
	v_cvt_f32_u32_e32 v0, s1
	v_readfirstlane_b32 s0, v211
	s_lshr_b32 s0, s0, 8
	s_mul_i32 s0, s0, s54
	v_rcp_iflag_f32_e32 v0, v0
	s_add_i32 s2, s52, s88
	s_sub_i32 s4, 0, s1
	s_add_i32 s0, s2, s0
	v_mul_f32_e32 v0, 0x4f7ffffe, v0
	v_cvt_u32_f32_e32 v0, v0
	s_addk_i32 s0, 0xff80
	s_ashr_i32 s2, s0, 31
	s_abs_i32 s0, s0
	v_readfirstlane_b32 s5, v0
	s_mul_i32 s4, s4, s5
	s_mul_hi_u32 s4, s5, s4
	s_add_i32 s5, s5, s4
	s_mul_hi_u32 s4, s0, s5
	s_mul_i32 s4, s4, s1
	s_sub_i32 s0, s0, s4
	s_sub_i32 s4, s0, s1
	s_cmp_ge_u32 s0, s1
	s_cselect_b32 s0, s4, s0
	s_sub_i32 s4, s0, s1
	s_cmp_ge_u32 s0, s1
	s_cselect_b32 s0, s4, s0
	s_xor_b32 s0, s0, s2
	s_sub_i32 s20, s0, s2
	s_mov_b32 s3, 0
	v_mov_b32_e32 v0, v210
	s_cmpk_gt_i32 s20, 0xc1f
	s_cbranch_scc1 .Lp1a_exit
	s_add_u32 s6, s86, 0x1180000
	s_addc_u32 s7, s87, 0
	s_add_u32 s21, s86, 0xd00000
	s_addc_u32 s22, s87, 0
	s_add_u32 s23, s86, 0xb00000
	s_addc_u32 s24, s87, 0
	s_add_u32 s25, s86, 0xa00000
	s_addc_u32 s26, s87, 0
	s_add_u32 s27, s86, 0x900000
	s_addc_u32 s28, s87, 0
	v_and_b32_e32 v2, 63, v0
	s_add_u32 s8, s86, 0x4200200
	v_ashrrev_i32_e32 v0, 4, v0
	s_addc_u32 s9, s87, 0
	v_lshlrev_b32_e32 v48, 4, v2
	v_mov_b32_e32 v49, 0
	v_and_b32_e32 v62, -4, v0
	v_lshl_add_u64 v[0:1], s[86:87], 0, v[48:49]
	s_mov_b64 s[4:5], 0x3200200
	s_add_u32 s10, s86, 0x2200200
	s_mov_b64 s[12:13], 0x1200200
	v_cmp_eq_u32_e64 s[0:1], 0, v213
	v_add_u32_e32 v63, 0xffffc000, v62
	v_lshl_add_u64 v[50:51], v[0:1], 0, s[4:5]
	v_cmp_eq_u32_e64 s[4:5], 0, v2
	s_addc_u32 s11, s87, 0
	v_lshl_add_u64 v[52:53], v[0:1], 0, s[12:13]
	v_lshl_add_u64 v[54:55], s[80:81], 0, v[48:49]
	v_lshl_add_u64 v[56:57], s[78:79], 0, v[48:49]
	s_movk_i32 s29, 0x104
	s_movk_i32 s30, 0x7fff
	s_movk_i32 s31, 0x1000
	s_movk_i32 s34, 0x2000
	s_movk_i32 s35, 0x3000
	v_mov_b32_e32 v64, 1
	v_mbcnt_hi_u32_b32 v65, -1, v212
	s_branch .Lp1a_354

; DI int my_tid() { int t = threadIdx.x & 255; asm volatile("" : "+v"(t)); return t; }
; DI void hsync() { hsync_impl(false); }
; DI float fexp2(float x) { return __builtin_amdgcn_exp2f(x); }
; DI void attn_item(const Params& p, int item, char* smem) {
;   char* ws = p.ws;
;   const u16* Q = (const u16*)(ws + WS_Q);
;   const u16* KS = (const u16*)(ws + WS_KS);
;   const u16* KW = (const u16*)(ws + WS_KW);
;   const u16* VTS = (const u16*)(ws + WS_VTS);
;   const u16* VTW = (const u16*)(ws + WS_VTW);
;   const u16* KCMP = (const u16*)(ws + WS_KCMP);
;   const u16* VCMPT = (const u16*)(ws + WS_VCMPT);
;   const float* NG = (const float*)(ws + WS_NG);
;   u16* ONSA = (u16*)p.out;
;   u16* KsB = (u16*)smem;
;   int pb = 0;
;     ...
;   unsigned* imp_s = (unsigned*)(KsB + 4 * 64 * 72);
;   unsigned char* sel8 = (unsigned char*)(imp_s + 32 * 65);
;   const int tid = my_tid(), lane = tid & 63, wave = tid >> 6;
;   const int lr = lane & 31, hh = lane >> 5;
;   const int bg = item & 7, q32 = 127 - (item >> 3);
;   const int b = bg >> 1, g = bg & 1;
;   const int t0 = q32 * 32;
;   const int head = g * 4 + wave;
;   const int t = t0 + lr;
;   const size_t row = (size_t)b * 4096 + t;
;   const int qb = t0 >> 6;
;   bf16x8 qf[4];
; #pragma unroll
;   for (int ks = 0; ks < 4; ++ks) qf[ks] = *(const bf16x8*)(Q + row * 512 + head * 64 + ks * 16 + hh * 8);
;   float* ot_s = (float*)(sel8 + 256) + wave * 32 * 64 + lane;
;   const float slope2 = fexp2(-(float)(head + 1)) * LOG2E;
;   const float gc = NG[row * 32 + head], gs = NG[row * 32 + 8 + head], gw = NG[row * 32 + 16 + head];
;   f32x16 O[2];
;   hsync();
;   for (int i = tid; i < 32 * 65; i += 256) imp_s[i] = 0u;
;   const int nct = t0 / 1024 + 1;
;   float m = -1e30f, l = 0.f;
;   KVRegs kvr;
;   kv_issue(kvr, KCMP + ((size_t)(bg * 256)) * 64, 64, VCMPT + (size_t)bg * 64 * 256, 256, tid);
; #pragma unroll 1
;   for (int c = 0; c < nct; ++c) {
;     kv_commit(kvr, Ks, Vts, tid);
;     const int cn = (c + 1 < nct) ? c + 1 : 0;
;     kv_issue(kvr, KCMP + ((size_t)(bg * 256 + 64 * cn)) * 64, 64, VCMPT + (size_t)bg * 64 * 256 + 64 * cn, 256, tid);
;     attend_tile<16, false, 1, 1>(Ks, Vts, qf, O, m, l, t - (31 + 1024 * c), slope2, true, 0.f, nullptr, 0, lr, hh);
.Lp1a_exit:
	s_cmpk_gt_i32 s94, 0x3ff
	s_cbranch_scc1 .LBB0_658
	v_readlane_b32 s0, v253, 34
	s_add_i32 s56, s88, 0x3ff
	v_readlane_b32 s14, v253, 48
	v_readlane_b32 s1, v253, 35
	v_readlane_b32 s15, v253, 49
	s_add_u32 s0, s14, 0x7200200
	s_addc_u32 s1, s15, 0
	v_readlane_b32 s2, v253, 36
	v_readlane_b32 s3, v253, 37
	v_readlane_b32 s4, v253, 38
	v_readlane_b32 s5, v253, 39
	v_readlane_b32 s6, v253, 40
	v_readlane_b32 s7, v253, 41
	v_readlane_b32 s8, v253, 42
	v_readlane_b32 s9, v253, 43
	v_readlane_b32 s10, v253, 44
	v_readlane_b32 s11, v253, 45
	v_readlane_b32 s12, v253, 46
	v_readlane_b32 s13, v253, 47
	v_writelane_b32 v253, s0, 57
	s_mov_b32 s18, 0
	s_mov_b32 s84, 0x42000000
	v_writelane_b32 v253, s1, 58
	s_add_u32 s0, s14, 0x8e00200
	v_writelane_b32 v253, s0, 59
	s_addc_u32 s0, s15, 0
	v_writelane_b32 v253, s0, 60
	s_add_u32 s0, s14, 0x9600200
	v_writelane_b32 v253, s0, 61
	s_addc_u32 s0, s15, 0
	v_writelane_b32 v253, s0, 62
	s_add_u32 s0, s14, 0x8a00200
	v_writelane_b32 v253, s0, 63
	s_addc_u32 s0, s15, 0
	v_writelane_b32 v252, s0, 0
	s_add_u32 s0, s14, 0x9200200
	v_writelane_b32 v252, s0, 1
	s_addc_u32 s0, s15, 0
	v_writelane_b32 v252, s0, 2
	s_add_u32 s0, s14, 0x9a00200
	s_addc_u32 s1, s15, 0
	v_writelane_b32 v252, s0, 3
	s_mov_b32 s58, 0x43000000
	s_mov_b32 s60, 0x43200000
	v_writelane_b32 v252, s1, 4
	s_add_u32 s0, s14, 0x9a80200
	s_addc_u32 s1, s15, 0
	v_writelane_b32 v252, s0, 5
	s_mov_b32 s64, 0x43800000
	s_mov_b32 s66, 0x43900000
	v_writelane_b32 v252, s1, 6
	s_add_i32 s0, s33, 0x9000
	v_writelane_b32 v252, s0, 7
	s_add_i32 s0, s33, 0x9004
	s_mov_b32 s48, 0x43c00000
	s_mov_b32 s50, 0x43d00000
	s_brev_b32 s52, 34
	s_mov_b32 s54, 0x44080000
	s_mov_b32 s40, 0x44200000
	s_mov_b32 s42, 0x44280000
	s_mov_b32 s44, 0x44400000
	s_mov_b32 s46, 0x44480000
	s_mov_b32 s72, 0x44600000
	s_mov_b32 s74, 0x44680000
	s_mov_b32 s68, 2.0
	s_mov_b32 s70, 0x41000000
	v_writelane_b32 v252, s0, 8
	s_add_i32 s0, s33, 0x8ff8
	s_mov_b32 s19, 0x41800000
	v_mov_b32_e32 v97, 0
	s_mov_b32 s85, 0x42400000
	s_mov_b32 s59, 0x43100000
	s_mov_b32 s61, 0x43300000
	s_mov_b32 s65, 0x43880000
	s_mov_b32 s67, 0x43980000
	s_mov_b32 s49, 0x43c80000
	s_mov_b32 s51, 0x43d80000
	s_mov_b32 s53, 0x44040000
	s_mov_b32 s55, 0x440c0000
	s_mov_b32 s41, 0x44240000
	s_mov_b32 s43, 0x442c0000
	s_mov_b32 s45, 0x44440000
	s_mov_b32 s47, 0x444c0000
	s_mov_b32 s73, 0x44640000
	s_mov_b32 s75, 0x446c0000
	v_mbcnt_hi_u32_b32 v101, -1, v212
	s_mov_b32 s69, 0x40400000
	s_mov_b32 s71, 0x41100000
	s_waitcnt vmcnt(1)
	v_mov_b32_e32 v154, 0xffffff80
	v_mov_b32_e32 v155, 0x7149f2ca
	v_writelane_b32 v252, s0, 9
	s_mov_b32 s95, 0xf149f2ca
	s_movk_i32 s96, 0x7f
	s_movk_i32 s97, 0x8f
	s_movk_i32 s6, 0x9f
	s_movk_i32 s7, 0xaf
	s_movk_i32 s34, 0xff
	s_movk_i32 s35, 0x10f
	s_movk_i32 s14, 0x11f
	s_movk_i32 s15, 0x12f
	s_movk_i32 s20, 0x17f
	s_movk_i32 s21, 0x18f
	s_movk_i32 s2, 0x19f
	s_movk_i32 s3, 0x1af
	s_movk_i32 s24, 0x1ff
	s_movk_i32 s25, 0x20f
	s_movk_i32 s36, 0x21f
	s_movk_i32 s37, 0x22f
	s_movk_i32 s12, 0x27f
	s_movk_i32 s13, 0x28f
	s_movk_i32 s22, 0x29f
	s_movk_i32 s23, 0x2af
	s_movk_i32 s16, 0x2ff
	s_movk_i32 s17, 0x30f
	s_movk_i32 s26, 0x31f
	s_movk_i32 s27, 0x32f
	s_movk_i32 s28, 0x37f
	s_movk_i32 s29, 0x38f
	s_movk_i32 s30, 0x39f
	s_movk_i32 s31, 0x3af
	s_mov_b32 s76, 0xefa18f08
	s_mov_b32 s77, 0x49800000
	s_mov_b32 s78, s18
	v_cmp_eq_u32_e64 s[4:5], 0, v213
	s_mov_b32 s83, 0x41880000
	s_mov_b32 s39, 0x42040000
	s_mov_b32 s87, 0x42440000
	v_writelane_b32 v252, s88, 10
	s_branch .LBB0_533

; DI int vb_n() { return (int)gridDim.x * 2; }
; DI void phase_prep(const Params& p, char* smem, int part, int vb) {
;     ...
;   } else {
;     const int NITEMS = 1024 + 1024 + 128 + 128 + 256 + 512 + 32;
;     for (int it0 = vb; it0 < NITEMS; it0 += vb_n()) {
;       int it = it0;
;       if (it < 1024) {
;         int row = it * 16 + wave * 4;
;         fp8_rows<4>(p.pu + (size_t)row * 1024, (unsigned char*)(ws + WS_UBF) + (size_t)row * 1024, (float*)(ws + WS_SU) + row, lane);
;         continue;
;       }
;       it -= 1024;
;       if (it < 1024) {
;         int row = it * 16 + wave * 4;
;         fp8_rows<4>(p.pv + (size_t)row * 1024, (unsigned char*)(ws + WS_VBF) + (size_t)row * 1024, (float*)(ws + WS_SV) + row, lane);
;         continue;
;       }
;       it -= 1024;
; __global__ void __launch_bounds__(512) fwd_megakernel(Params p) {
;     ...
;   phase_mix(p, hsm);
;   xcd_barrier(xb);
;   phase_merge(p, smem);
;   xcd_barrier(xb);
.LBB0_752:
	v_readfirstlane_b32 s0, v211
	s_nop 0
	s_lshr_b32 s0, s0, 8
	s_cmp_eq_u32 s0, 0
	s_cbranch_scc1 .Lp1b_exit
	v_readlane_b32 s74, v253, 36
	v_readlane_b32 s75, v253, 37
	v_readlane_b32 s76, v253, 38
	v_readlane_b32 s77, v253, 39
	v_readlane_b32 s78, v253, 40
	v_readlane_b32 s79, v253, 41
	v_readlane_b32 s80, v253, 42
	v_readlane_b32 s81, v253, 43
	v_readlane_b32 s86, v253, 48
	v_readlane_b32 s87, v253, 49
	v_readlane_b32 s52, v253, 56
	v_readlane_b32 s54, v253, 54
	s_nop 3
	s_abs_i32 s1, s88
	v_cvt_f32_u32_e32 v0, s1
	v_readfirstlane_b32 s0, v211
	s_lshr_b32 s0, s0, 8
	s_mul_i32 s0, s0, s54
	v_rcp_iflag_f32_e32 v0, v0
	s_add_i32 s2, s52, s88
	s_sub_i32 s4, 0, s1
	s_add_i32 s0, s2, s0
	v_mul_f32_e32 v0, 0x4f7ffffe, v0
	v_cvt_u32_f32_e32 v0, v0
	s_addk_i32 s0, 0xff80
	s_ashr_i32 s2, s0, 31
	s_abs_i32 s0, s0
	v_readfirstlane_b32 s5, v0
	s_mul_i32 s4, s4, s5
	s_mul_hi_u32 s4, s5, s4
	s_add_i32 s5, s5, s4
	s_mul_hi_u32 s4, s0, s5
	s_mul_i32 s4, s4, s1
	s_sub_i32 s0, s0, s4
	s_sub_i32 s4, s0, s1
	s_cmp_ge_u32 s0, s1
	s_cselect_b32 s0, s4, s0
	s_sub_i32 s4, s0, s1
	s_cmp_ge_u32 s0, s1
	s_cselect_b32 s0, s4, s0
	s_xor_b32 s0, s0, s2
	s_sub_i32 s20, s0, s2
	s_mov_b32 s3, 0
	v_mov_b32_e32 v0, v210
	s_cmpk_gt_i32 s20, 0xc1f
	s_cbranch_scc1 .Lp1b_exit
	s_add_u32 s6, s86, 0x1180000
	s_addc_u32 s7, s87, 0
	s_add_u32 s21, s86, 0xd00000
	s_addc_u32 s22, s87, 0
	s_add_u32 s23, s86, 0xb00000
	s_addc_u32 s24, s87, 0
	s_add_u32 s25, s86, 0xa00000
	s_addc_u32 s26, s87, 0
	s_add_u32 s27, s86, 0x900000
	s_addc_u32 s28, s87, 0
	v_and_b32_e32 v2, 63, v0
	s_add_u32 s8, s86, 0x4200200
	v_ashrrev_i32_e32 v0, 4, v0
	s_addc_u32 s9, s87, 0
	v_lshlrev_b32_e32 v48, 4, v2
	v_mov_b32_e32 v49, 0
	v_and_b32_e32 v62, -4, v0
	v_lshl_add_u64 v[0:1], s[86:87], 0, v[48:49]
	s_mov_b64 s[4:5], 0x3200200
	s_add_u32 s10, s86, 0x2200200
	s_mov_b64 s[12:13], 0x1200200
	v_cmp_eq_u32_e64 s[0:1], 0, v213
	v_add_u32_e32 v63, 0xffffc000, v62
	v_lshl_add_u64 v[50:51], v[0:1], 0, s[4:5]
	v_cmp_eq_u32_e64 s[4:5], 0, v2
	s_addc_u32 s11, s87, 0
	v_lshl_add_u64 v[52:53], v[0:1], 0, s[12:13]
	v_lshl_add_u64 v[54:55], s[80:81], 0, v[48:49]
	v_lshl_add_u64 v[56:57], s[78:79], 0, v[48:49]
	s_movk_i32 s29, 0x104
	s_movk_i32 s30, 0x7fff
	s_movk_i32 s31, 0x1000
	s_movk_i32 s34, 0x2000
	s_movk_i32 s35, 0x3000
	v_mov_b32_e32 v64, 1
	v_mbcnt_hi_u32_b32 v65, -1, v212
	s_branch .Lp1b_354

; __device__ __forceinline__ unsigned xb_ld(unsigned* p)              { return __hip_atomic_load(p, __ATOMIC_RELAXED, __HIP_MEMORY_SCOPE_AGENT); }
; __device__ __forceinline__ unsigned xb_add(unsigned* p, unsigned v) { return __hip_atomic_fetch_add(p, v, __ATOMIC_RELAXED, __HIP_MEMORY_SCOPE_AGENT); }
; __device__ __forceinline__ void xcd_barrier_complete(unsigned* bar, unsigned x, unsigned& nloc, unsigned& nx) {
;     const unsigned G = gridDim.x * gridDim.y * gridDim.z;
;     unsigned sum, cnt, mine, sp = 0u;
;     for (;;) {
;         sum = 0u; cnt = 0u; mine = 0u;
; #pragma unroll
;         for (unsigned j = 0; j < 16; ++j) { const unsigned c = xb_ld(&bar[XB_XCNT(j)]); sum += c; cnt += (c > 0u) ? 1u : 0u; mine = (j == x) ? c : mine; }
; __device__ __forceinline__ void xcd_barrier(const XcdBarrier& b) {
;     asm volatile("s_waitcnt vmcnt(0)" ::: "memory");
;     __syncthreads();
;     if (threadIdx.x == 0) {
;         unsigned* bar = b.bar;
;         __builtin_amdgcn_s_waitcnt(0);
;         unsigned nloc = b.st[0], nx = b.st[1];
;         if (nloc == 0u) { xcd_barrier_complete(bar, b.x, nloc, nx); b.st[0] = nloc; b.st[1] = nx; }
;         const unsigned old = xb_add(&bar[XB_XSUB(b.x)], 1u);
;         const unsigned gen = old / nloc;
;         if (old + 1u == (gen + 1u) * nloc) {
.Lp1b_exit:
	v_readlane_b32 s74, v253, 44
	v_readlane_b32 s75, v253, 45
	v_readlane_b32 s76, v253, 46
	v_readlane_b32 s77, v253, 47
	v_readlane_b32 s78, v253, 48
	v_readlane_b32 s79, v253, 49
	s_nop 3
	s_waitcnt vmcnt(0)
	s_waitcnt lgkmcnt(0)
	s_barrier
	s_and_saveexec_b64 s[0:1], s[68:69]
	s_cbranch_execz .LBB0_804
	v_mov_b32_e32 v0, 0
	s_waitcnt vmcnt(0) expcnt(0) lgkmcnt(0)
	ds_read_b32 v2, v0 offset:16
	ds_read_b32 v1, v0 offset:20
	s_waitcnt lgkmcnt(1)
	v_cmp_ne_u32_e32 vcc, 0, v2
	s_cbranch_vccnz .LBB0_768
	s_add_u32 s2, s78, 0xec80400
	s_addc_u32 s3, s79, 0
	s_add_u32 s4, s78, 0xec80600
	s_addc_u32 s5, s79, 0
	s_add_u32 s6, s78, 0xec80700
	s_addc_u32 s7, s79, 0
	s_add_u32 s8, s78, 0xec80800
	s_addc_u32 s9, s79, 0
	s_add_u32 s10, s78, 0xec80900
	s_addc_u32 s11, s79, 0
	s_add_u32 s12, s78, 0xec80a00
	s_addc_u32 s13, s79, 0
	s_add_u32 s14, s78, 0xec80b00
	s_addc_u32 s15, s79, 0
	s_add_u32 s16, s78, 0xec80c00
	s_addc_u32 s17, s79, 0
	s_add_u32 s18, s78, 0xec80d00
	s_addc_u32 s19, s79, 0
	s_add_u32 s20, s78, 0xec80e00
	s_addc_u32 s21, s79, 0
	s_add_u32 s22, s78, 0xec80f00
	s_addc_u32 s23, s79, 0
	s_add_u32 s24, s78, 0xec81000
	s_addc_u32 s25, s79, 0
	s_add_u32 s26, s78, 0xec81100
	s_addc_u32 s27, s79, 0
	s_add_u32 s28, s78, 0xec81200
	s_addc_u32 s29, s79, 0
	s_add_u32 s30, s78, 0xec81300
	s_addc_u32 s31, s79, 0
	s_add_u32 s34, s78, 0xec81400
	s_addc_u32 s35, s79, 0
	s_mul_i32 s44, s61, s67
	s_add_u32 s36, s78, 0xec81500
	s_mul_i32 s44, s44, s60
	s_addc_u32 s37, s79, 0
	s_mov_b32 s45, 1
	s_branch .LBB0_756
